# phase 1 weight-conversion tiles assigned by per-workgroup load: 6 rounds for all PLE workgroups, +2 tiles for those with two PLE tiles, last 192 tiles to the 6-tile GEMM workgroups
# speedup vs baseline: 1.0061x; 1.0061x over previous
.LBB0_522:
	s_movk_i32 s98, 0x940
	s_mov_b32 s99, 0
	s_cmpk_lt_i32 s41, 0x80
	s_cbranch_scc1 .Lwc_go
	s_add_i32 s99, s41, 0x400
	s_branch .Lwc_go
.Lwc_again:
	s_cmp_eq_u32 s99, 0
	s_cbranch_scc1 .LBB0_699
	s_add_u32 s8, s92, 0x2500000
	s_addc_u32 s9, s93, 0
	s_mov_b32 s41, s99
	s_mov_b32 s99, 0
	s_movk_i32 s40, 64
	s_movk_i32 s98, 0x9c0
	s_branch .Lwc_go
.Lwc_heavy:
	s_add_u32 s8, s92, 0x2500000
	s_addc_u32 s9, s93, 0
	s_movk_i32 s40, 64
	s_add_i32 s41, s97, 0x500
	s_movk_i32 s98, 0xa80
	s_mov_b32 s99, 0
